# P0 gate-weight staging: 16 gather loads per thread issued up-front (was 4 serialized groups)
# baseline (speedup 1.0000x reference)
; DI int otid() { int t = __builtin_amdgcn_workitem_id_x(); asm volatile("" : "+v"(t)); return t; }
; DI void ln_in_rows(const float* __restrict__ src, const float* __restrict__ g, const float* __restrict__ bta, const float* __restrict__ w_in, u16* __restrict__ dst, float* __restrict__ G, float* Wg) {
;     ...
;   for (int e = otid(); e < 8192; e += 512) Wg[e] = w_in[(size_t)(e >> 3) * 3592 + 3584 + (e & 7)];
;   __syncthreads();
.LBB0_153:
	s_or_b64 exec, exec, s[6:7]
	v_mov_b32_e32 v90, v222
	v_mov_b32_e32 v1, v222
	v_mov_b32_e32 v2, v222
	s_movk_i32 s0, 0x2000
	s_nop 0
	v_cmp_gt_i32_e32 vcc, s0, v2
	s_and_saveexec_b64 s[0:1], vcc
	s_cbranch_execz .LBB0_165
	v_and_b32_e32 v4, 7, v2
	v_lshlrev_b32_e32 v72, 2, v4
	v_mov_b32_e32 v73, 0
	v_mov_b64_e32 v[74:75], s[60:61]
	v_lshl_add_u64 v[74:75], v[74:75], 0, v[72:73]
	s_mov_b64 s[12:13], 0x3800
	v_lshl_add_u64 v[74:75], v[74:75], 0, s[12:13]
	s_movk_i32 s3, 0x3820
	v_ashrrev_i32_e32 v5, 3, v2
	v_lshlrev_b32_e32 v78, 2, v2
	v_mad_i64_i32 v[76:77], s[12:13], v5, s3, v[74:75]
	global_load_dword v56, v[76:77], off
	v_add_u32_e32 v5, 64, v5
	v_mad_i64_i32 v[76:77], s[12:13], v5, s3, v[74:75]
	global_load_dword v57, v[76:77], off
	v_add_u32_e32 v5, 64, v5
	v_mad_i64_i32 v[76:77], s[12:13], v5, s3, v[74:75]
	global_load_dword v58, v[76:77], off
	v_add_u32_e32 v5, 64, v5
	v_mad_i64_i32 v[76:77], s[12:13], v5, s3, v[74:75]
	global_load_dword v59, v[76:77], off
	v_add_u32_e32 v5, 64, v5
	v_mad_i64_i32 v[76:77], s[12:13], v5, s3, v[74:75]
	global_load_dword v60, v[76:77], off
	v_add_u32_e32 v5, 64, v5
	v_mad_i64_i32 v[76:77], s[12:13], v5, s3, v[74:75]
	global_load_dword v61, v[76:77], off
	v_add_u32_e32 v5, 64, v5
	v_mad_i64_i32 v[76:77], s[12:13], v5, s3, v[74:75]
	global_load_dword v62, v[76:77], off
	v_add_u32_e32 v5, 64, v5
	v_mad_i64_i32 v[76:77], s[12:13], v5, s3, v[74:75]
	global_load_dword v63, v[76:77], off
	v_add_u32_e32 v5, 64, v5
	v_mad_i64_i32 v[76:77], s[12:13], v5, s3, v[74:75]
	global_load_dword v64, v[76:77], off
	v_add_u32_e32 v5, 64, v5
	v_mad_i64_i32 v[76:77], s[12:13], v5, s3, v[74:75]
	global_load_dword v65, v[76:77], off
	v_add_u32_e32 v5, 64, v5
	v_mad_i64_i32 v[76:77], s[12:13], v5, s3, v[74:75]
	global_load_dword v66, v[76:77], off
	v_add_u32_e32 v5, 64, v5
	v_mad_i64_i32 v[76:77], s[12:13], v5, s3, v[74:75]
	global_load_dword v67, v[76:77], off
	v_add_u32_e32 v5, 64, v5
	v_mad_i64_i32 v[76:77], s[12:13], v5, s3, v[74:75]
	global_load_dword v68, v[76:77], off
	v_add_u32_e32 v5, 64, v5
	v_mad_i64_i32 v[76:77], s[12:13], v5, s3, v[74:75]
	global_load_dword v69, v[76:77], off
	v_add_u32_e32 v5, 64, v5
	v_mad_i64_i32 v[76:77], s[12:13], v5, s3, v[74:75]
	global_load_dword v70, v[76:77], off
	v_add_u32_e32 v5, 64, v5
	v_mad_i64_i32 v[76:77], s[12:13], v5, s3, v[74:75]
	global_load_dword v71, v[76:77], off
	s_waitcnt vmcnt(15)
	ds_write_b32 v78, v56
	s_waitcnt vmcnt(14)
	ds_write_b32 v78, v57 offset:2048
	s_waitcnt vmcnt(13)
	ds_write_b32 v78, v58 offset:4096
	s_waitcnt vmcnt(12)
	ds_write_b32 v78, v59 offset:6144
	s_waitcnt vmcnt(11)
	ds_write_b32 v78, v60 offset:8192
	s_waitcnt vmcnt(10)
	ds_write_b32 v78, v61 offset:10240
	s_waitcnt vmcnt(9)
	ds_write_b32 v78, v62 offset:12288
	s_waitcnt vmcnt(8)
	ds_write_b32 v78, v63 offset:14336
	s_waitcnt vmcnt(7)
	ds_write_b32 v78, v64 offset:16384
	s_waitcnt vmcnt(6)
	ds_write_b32 v78, v65 offset:18432
	s_waitcnt vmcnt(5)
	ds_write_b32 v78, v66 offset:20480
	s_waitcnt vmcnt(4)
	ds_write_b32 v78, v67 offset:22528
	s_waitcnt vmcnt(3)
	ds_write_b32 v78, v68 offset:24576
	s_waitcnt vmcnt(2)
	ds_write_b32 v78, v69 offset:26624
	s_waitcnt vmcnt(1)
	ds_write_b32 v78, v70 offset:28672
	s_waitcnt vmcnt(0)
	ds_write_b32 v78, v71 offset:30720
